# SSD chunk loop: y + D*x reads x from the LDS tile instead of 4 serialized global reloads (no vmcnt(0) in the loop; next chunk prefetch stays in flight)
# speedup vs baseline: 1.0118x; 1.0008x over previous
; __device__ __forceinline__ unsigned pk2(float lo, float hi) { unsigned r; asm("v_cvt_pk_bf16_f32 %0, %1, %2" : "=v"(r) : "v"(lo), "v"(hi)); return r; }
; __global__ void __launch_bounds__(NWAVES * 64, 2) fwd(Args args_unused) {
;     ...
;                         { const size_t row = r0 + lrow;
; #pragma unroll
;                           for (int pt = 0; pt < 4; ++pt) { const v2u xg = *(const v2u*)(XBCV + row * 1536 + hd * 64 + 16 * pt + 4 * q4);
;                               f32x4 y = yacc[pt]; y.x += Dsk * bflo(xg.x); y.y += Dsk * bfhi(xg.x); y.z += Dsk * bflo(xg.y); y.w += Dsk * bfhi(xg.y);
;                               v2u yw; yw.x = pk2(y.x, y.y); yw.y = pk2(y.z, y.w); *(v2u*)(YS + row * DM + hd * 64 + 16 * pt + 4 * q4) = yw; } }
;                         { const float elast = __expf(alast);
; #pragma unroll
;                           for (int pt = 0; pt < 4; ++pt) hacc[pt] = hacc[pt] * elast;
; #pragma unroll
;                           for (int ks = 0; ks < 4; ++ks) { const v2u b0 = tr_read(Bw, ST, 32 * ks + 8 * q4, 16 * w, qq), b1 = tr_read(Bw, ST, 32 * ks + 8 * q4 + 4, 16 * w, qq);
;                               v4u bw; bw.x = b0.x; bw.y = b0.y; bw.z = b1.x; bw.w = b1.y; const bf16x8 bfb = __builtin_bit_cast(bf16x8, bw);
; #pragma unroll
;                               for (int pt = 0; pt < 4; ++pt) { const v2u a0 = tr_read(xs, SX, 32 * ks + 8 * q4, 16 * pt, qq), a1 = tr_read(xs, SX, 32 * ks + 8 * q4 + 4, 16 * pt, qq);
;                                   v4u aw; aw.x = a0.x; aw.y = a0.y; aw.z = a1.x; aw.w = a1.y; hacc[pt] = __builtin_amdgcn_mfma_f32_16x16x32_bf16(__builtin_bit_cast(bf16x8, aw), bfb, hacc[pt], 0, 0, 0); } } }
.LBB0_1619:
	v_mbcnt_lo_u32_b32 v255, -1, 0
	v_mbcnt_hi_u32_b32 v255, -1, v255
	v_readfirstlane_b32 s98, v0
	v_and_b32_e32 v250, 15, v255
	v_lshrrev_b32_e32 v255, 4, v255
	s_lshr_b32 s98, s98, 6
	s_lshl_b32 s98, s98, 4
	v_lshlrev_b32_e32 v255, 3, v255
	s_movk_i32 s99, 0x90
	v_add_u32_e32 v250, s98, v250
	v_mad_u32_u24 v255, v250, s99, v255
	v_lshl_add_u64 v[68:69], s[94:95], 0, v[180:181]
	s_mov_b64 s[24:25], 0x2000
	s_add_i32 s23, s23, -1
	v_lshl_add_u64 v[178:179], v[178:179], 0, s[24:25]
	s_mov_b64 s[24:25], 0x40000
	v_lshl_add_u64 v[166:167], v[166:167], 0, s[20:21]
	v_lshl_add_u64 v[168:169], v[168:169], 0, s[20:21]
	v_lshl_add_u64 v[170:171], v[170:171], 0, s[20:21]
	v_lshl_add_u64 v[172:173], v[172:173], 0, s[20:21]
	v_lshl_add_u64 v[174:175], v[174:175], 0, s[20:21]
	v_lshl_add_u64 v[176:177], v[176:177], 0, s[20:21]
	v_lshl_add_u64 v[180:181], v[180:181], 0, s[24:25]
	v_lshl_add_u64 v[182:183], v[182:183], 0, s[20:21]
	s_cmp_eq_u32 s23, 0
	ds_read_b64 v[250:251], v255
	ds_read_b64 v[252:253], v255 offset:32
	s_waitcnt lgkmcnt(0)
	v_lshlrev_b32_e32 v80, 16, v250
	v_and_b32_e32 v78, 0xffff0000, v250
	v_fma_f32 v75, v219, v78, v75
	v_lshlrev_b32_e32 v78, 16, v251
	v_fma_f32 v74, v219, v80, v74
	v_fma_f32 v76, v219, v78, v76
	v_and_b32_e32 v78, 0xffff0000, v251
	v_fmac_f32_e32 v77, v219, v78
	v_cvt_pk_bf16_f32 v74, v74, v75
	v_cvt_pk_bf16_f32 v75, v76, v77
	global_store_dwordx2 v[68:69], v[74:75], off offset:-64
	v_lshlrev_b32_e32 v80, 16, v252
	v_and_b32_e32 v78, 0xffff0000, v252
	v_fma_f32 v71, v219, v78, v71
	v_lshlrev_b32_e32 v78, 16, v253
	v_fma_f32 v70, v219, v80, v70
	v_fma_f32 v72, v219, v78, v72
	v_and_b32_e32 v78, 0xffff0000, v253
	v_fmac_f32_e32 v73, v219, v78
	v_cvt_pk_bf16_f32 v70, v70, v71
	v_cvt_pk_bf16_f32 v71, v72, v73
	global_store_dwordx2 v[68:69], v[70:71], off offset:-32
	ds_read_b64 v[250:251], v255 offset:64
	ds_read_b64 v[252:253], v255 offset:96
	s_waitcnt lgkmcnt(0)
	v_lshlrev_b32_e32 v80, 16, v250
	v_and_b32_e32 v78, 0xffff0000, v250
	v_fma_f32 v63, v219, v78, v63
	v_lshlrev_b32_e32 v78, 16, v251
	v_fma_f32 v62, v219, v80, v62
	v_fma_f32 v64, v219, v78, v64
	v_and_b32_e32 v78, 0xffff0000, v251
	v_fmac_f32_e32 v65, v219, v78
	v_cvt_pk_bf16_f32 v62, v62, v63
	v_cvt_pk_bf16_f32 v63, v64, v65
	global_store_dwordx2 v[68:69], v[62:63], off
	v_add_u32_e32 v70, v190, v207
	v_lshlrev_b32_e32 v80, 16, v252
	v_and_b32_e32 v78, 0xffff0000, v252
	v_fma_f32 v59, v219, v78, v59
	v_lshlrev_b32_e32 v78, 16, v253
	v_fma_f32 v58, v219, v80, v58
	v_fma_f32 v60, v219, v78, v60
	v_and_b32_e32 v78, 0xffff0000, v253
	v_fmac_f32_e32 v61, v219, v78
	v_cvt_pk_bf16_f32 v58, v58, v59
	v_cvt_pk_bf16_f32 v59, v60, v61
	global_store_dwordx2 v[68:69], v[58:59], off offset:32
	v_mul_f32_e32 v58, 0x3fb8aa3b, v222
	v_exp_f32_e32 v58, v58
	s_nop 0
	v_pk_mul_f32 v[48:49], v[58:59], v[48:49] op_sel_hi:[0,1]
	v_pk_mul_f32 v[46:47], v[58:59], v[46:47] op_sel_hi:[0,1]
	v_pk_mul_f32 v[52:53], v[58:59], v[52:53] op_sel_hi:[0,1]
	v_pk_mul_f32 v[50:51], v[58:59], v[50:51] op_sel_hi:[0,1]
	v_pk_mul_f32 v[56:57], v[58:59], v[56:57] op_sel_hi:[0,1]
	v_pk_mul_f32 v[54:55], v[58:59], v[54:55] op_sel_hi:[0,1]
	v_pk_mul_f32 v[44:45], v[58:59], v[44:45] op_sel_hi:[0,1]
	v_pk_mul_f32 v[42:43], v[58:59], v[42:43] op_sel_hi:[0,1]
	ds_read_b64_tr_b16 v[58:59], v213 offset:53248
	ds_read_b64_tr_b16 v[60:61], v213 offset:54336
	ds_read_b64_tr_b16 v[62:63], v70
	ds_read_b64_tr_b16 v[66:67], v70 offset:32
	ds_read_b64_tr_b16 v[64:65], v214
	ds_read_b64_tr_b16 v[68:69], v214 offset:32
	s_waitcnt lgkmcnt(1)
	v_mfma_f32_16x16x32_bf16 v[46:49], v[62:65], v[58:61], v[46:49]
	ds_read_b64_tr_b16 v[62:63], v70 offset:64
	ds_read_b64_tr_b16 v[64:65], v214 offset:64
	s_waitcnt lgkmcnt(0)
	v_mfma_f32_16x16x32_bf16 v[54:57], v[62:65], v[58:61], v[54:57]
	ds_read_b64_tr_b16 v[62:63], v70 offset:96
	ds_read_b64_tr_b16 v[64:65], v214 offset:96
	v_mfma_f32_16x16x32_bf16 v[50:53], v[66:69], v[58:61], v[50:53]
	s_waitcnt lgkmcnt(0)
	v_mfma_f32_16x16x32_bf16 v[42:45], v[62:65], v[58:61], v[42:45]
	ds_read_b64_tr_b16 v[58:59], v213 offset:61952
	ds_read_b64_tr_b16 v[60:61], v213 offset:63040
	ds_read_b64_tr_b16 v[62:63], v70 offset:4608
	ds_read_b64_tr_b16 v[64:65], v214 offset:4608
	s_waitcnt lgkmcnt(0)
	v_mfma_f32_16x16x32_bf16 v[46:49], v[62:65], v[58:61], v[46:49]
	ds_read_b64_tr_b16 v[62:63], v70 offset:4640
	ds_read_b64_tr_b16 v[64:65], v214 offset:4640
	s_waitcnt lgkmcnt(0)
	v_mfma_f32_16x16x32_bf16 v[50:53], v[62:65], v[58:61], v[50:53]
	ds_read_b64_tr_b16 v[62:63], v70 offset:4672
	ds_read_b64_tr_b16 v[64:65], v214 offset:4672
	s_waitcnt lgkmcnt(0)
	v_mfma_f32_16x16x32_bf16 v[54:57], v[62:65], v[58:61], v[54:57]
	ds_read_b64_tr_b16 v[62:63], v70 offset:4704
	ds_read_b64_tr_b16 v[64:65], v214 offset:4704
	s_waitcnt lgkmcnt(0)
	v_mfma_f32_16x16x32_bf16 v[42:45], v[62:65], v[58:61], v[42:45]
	ds_read_b64_tr_b16 v[58:59], v215 offset:53248
	ds_read_b64_tr_b16 v[60:61], v215 offset:54336
	ds_read_b64_tr_b16 v[62:63], v70 offset:9216
	ds_read_b64_tr_b16 v[64:65], v214 offset:9216
	s_waitcnt lgkmcnt(0)
	v_mfma_f32_16x16x32_bf16 v[46:49], v[62:65], v[58:61], v[46:49]
	ds_read_b64_tr_b16 v[62:63], v70 offset:9248
	ds_read_b64_tr_b16 v[64:65], v214 offset:9248
	s_waitcnt lgkmcnt(0)
	v_mfma_f32_16x16x32_bf16 v[50:53], v[62:65], v[58:61], v[50:53]
	ds_read_b64_tr_b16 v[62:63], v70 offset:9280
	ds_read_b64_tr_b16 v[64:65], v214 offset:9280
	s_waitcnt lgkmcnt(0)
	v_mfma_f32_16x16x32_bf16 v[54:57], v[62:65], v[58:61], v[54:57]
	ds_read_b64_tr_b16 v[62:63], v70 offset:9312
	ds_read_b64_tr_b16 v[64:65], v214 offset:9312
	s_waitcnt lgkmcnt(0)
	v_mfma_f32_16x16x32_bf16 v[42:45], v[62:65], v[58:61], v[42:45]
	ds_read_b64_tr_b16 v[58:59], v215 offset:61952
	ds_read_b64_tr_b16 v[60:61], v215 offset:63040
	ds_read_b64_tr_b16 v[62:63], v70 offset:13824
	ds_read_b64_tr_b16 v[64:65], v214 offset:13824
	s_waitcnt lgkmcnt(0)
	v_mfma_f32_16x16x32_bf16 v[46:49], v[62:65], v[58:61], v[46:49]
	ds_read_b64_tr_b16 v[62:63], v70 offset:13856
	ds_read_b64_tr_b16 v[64:65], v214 offset:13856
	s_waitcnt lgkmcnt(0)
	v_mfma_f32_16x16x32_bf16 v[50:53], v[62:65], v[58:61], v[50:53]
	ds_read_b64_tr_b16 v[62:63], v70 offset:13888
	ds_read_b64_tr_b16 v[64:65], v214 offset:13888
	s_waitcnt lgkmcnt(0)
	v_mfma_f32_16x16x32_bf16 v[54:57], v[62:65], v[58:61], v[54:57]
	ds_read_b64_tr_b16 v[62:63], v70 offset:13920
	ds_read_b64_tr_b16 v[64:65], v214 offset:13920
	s_waitcnt lgkmcnt(0)
	v_mfma_f32_16x16x32_bf16 v[42:45], v[62:65], v[58:61], v[42:45]
	s_cbranch_scc1 .LBB0_1615

; __device__ __forceinline__ unsigned pk2(float lo, float hi) { unsigned r; asm("v_cvt_pk_bf16_f32 %0, %1, %2" : "=v"(r) : "v"(lo), "v"(hi)); return r; }
; __global__ void __launch_bounds__(NWAVES * 64, 2) fwd(Args args_unused) {
;     ...
;                         { const size_t row = r0 + lrow;
; #pragma unroll
;                           for (int pt = 0; pt < 4; ++pt) { const v2u xg = *(const v2u*)(XBCV + row * 1536 + hd * 64 + 16 * pt + 4 * q4);
;                               f32x4 y = yacc[pt]; y.x += Dsk * bflo(xg.x); y.y += Dsk * bfhi(xg.x); y.z += Dsk * bflo(xg.y); y.w += Dsk * bfhi(xg.y);
;                               v2u yw; yw.x = pk2(y.x, y.y); yw.y = pk2(y.z, y.w); *(v2u*)(YS + row * DM + hd * 64 + 16 * pt + 4 * q4) = yw; } }
;                         { const float elast = __expf(alast);
; #pragma unroll
;                           for (int pt = 0; pt < 4; ++pt) hacc[pt] = hacc[pt] * elast;
; #pragma unroll
;                           for (int ks = 0; ks < 4; ++ks) { const v2u b0 = tr_read(Bw, ST, 32 * ks + 8 * q4, 16 * w, qq), b1 = tr_read(Bw, ST, 32 * ks + 8 * q4 + 4, 16 * w, qq);
;                               v4u bw; bw.x = b0.x; bw.y = b0.y; bw.z = b1.x; bw.w = b1.y; const bf16x8 bfb = __builtin_bit_cast(bf16x8, bw);
; #pragma unroll
;                               for (int pt = 0; pt < 4; ++pt) { const v2u a0 = tr_read(xs, SX, 32 * ks + 8 * q4, 16 * pt, qq), a1 = tr_read(xs, SX, 32 * ks + 8 * q4 + 4, 16 * pt, qq);
;                                   v4u aw; aw.x = a0.x; aw.y = a0.y; aw.z = a1.x; aw.w = a1.y; hacc[pt] = __builtin_amdgcn_mfma_f32_16x16x32_bf16(__builtin_bit_cast(bf16x8, aw), bfb, hacc[pt], 0, 0, 0); } } }
.LBB0_3643:
	v_mbcnt_lo_u32_b32 v255, -1, 0
	v_mbcnt_hi_u32_b32 v255, -1, v255
	v_readfirstlane_b32 s98, v0
	v_and_b32_e32 v250, 15, v255
	v_lshrrev_b32_e32 v255, 4, v255
	s_lshr_b32 s98, s98, 6
	s_lshl_b32 s98, s98, 4
	v_lshlrev_b32_e32 v255, 3, v255
	s_movk_i32 s99, 0x90
	v_add_u32_e32 v250, s98, v250
	v_mad_u32_u24 v255, v250, s99, v255
	v_lshl_add_u64 v[68:69], s[94:95], 0, v[180:181]
	s_mov_b64 s[24:25], 0x2000
	s_add_i32 s23, s23, -1
	v_lshl_add_u64 v[166:167], v[166:167], 0, s[24:25]
	s_mov_b64 s[24:25], 0x40000
	v_lshl_add_u64 v[168:169], v[168:169], 0, s[20:21]
	v_lshl_add_u64 v[170:171], v[170:171], 0, s[20:21]
	v_lshl_add_u64 v[172:173], v[172:173], 0, s[20:21]
	v_lshl_add_u64 v[174:175], v[174:175], 0, s[20:21]
	v_lshl_add_u64 v[176:177], v[176:177], 0, s[20:21]
	v_lshl_add_u64 v[178:179], v[178:179], 0, s[20:21]
	v_lshl_add_u64 v[180:181], v[180:181], 0, s[24:25]
	v_lshl_add_u64 v[182:183], v[182:183], 0, s[20:21]
	s_cmp_lg_u32 s23, 0
	ds_read_b64 v[250:251], v255
	ds_read_b64 v[252:253], v255 offset:32
	s_waitcnt lgkmcnt(0)
	v_lshlrev_b32_e32 v80, 16, v250
	v_and_b32_e32 v78, 0xffff0000, v250
	v_fma_f32 v75, v219, v78, v75
	v_lshlrev_b32_e32 v78, 16, v251
	v_fma_f32 v74, v219, v80, v74
	v_fma_f32 v76, v219, v78, v76
	v_and_b32_e32 v78, 0xffff0000, v251
	v_fmac_f32_e32 v77, v219, v78
	v_cvt_pk_bf16_f32 v74, v74, v75
	v_cvt_pk_bf16_f32 v75, v76, v77
	global_store_dwordx2 v[68:69], v[74:75], off offset:-64
	v_lshlrev_b32_e32 v80, 16, v252
	v_and_b32_e32 v78, 0xffff0000, v252
	v_fma_f32 v71, v219, v78, v71
	v_lshlrev_b32_e32 v78, 16, v253
	v_fma_f32 v70, v219, v80, v70
	v_fma_f32 v72, v219, v78, v72
	v_and_b32_e32 v78, 0xffff0000, v253
	v_fmac_f32_e32 v73, v219, v78
	v_cvt_pk_bf16_f32 v70, v70, v71
	v_cvt_pk_bf16_f32 v71, v72, v73
	global_store_dwordx2 v[68:69], v[70:71], off offset:-32
	ds_read_b64 v[250:251], v255 offset:64
	ds_read_b64 v[252:253], v255 offset:96
	s_waitcnt lgkmcnt(0)
	v_lshlrev_b32_e32 v80, 16, v250
	v_and_b32_e32 v78, 0xffff0000, v250
	v_fma_f32 v63, v219, v78, v63
	v_lshlrev_b32_e32 v78, 16, v251
	v_fma_f32 v62, v219, v80, v62
	v_fma_f32 v64, v219, v78, v64
	v_and_b32_e32 v78, 0xffff0000, v251
	v_fmac_f32_e32 v65, v219, v78
	v_cvt_pk_bf16_f32 v62, v62, v63
	v_cvt_pk_bf16_f32 v63, v64, v65
	global_store_dwordx2 v[68:69], v[62:63], off
	v_add_u32_e32 v70, v190, v207
	v_lshlrev_b32_e32 v80, 16, v252
	v_and_b32_e32 v78, 0xffff0000, v252
	v_fma_f32 v59, v219, v78, v59
	v_lshlrev_b32_e32 v78, 16, v253
	v_fma_f32 v58, v219, v80, v58
	v_fma_f32 v60, v219, v78, v60
	v_and_b32_e32 v78, 0xffff0000, v253
	v_fmac_f32_e32 v61, v219, v78
	v_cvt_pk_bf16_f32 v58, v58, v59
	v_cvt_pk_bf16_f32 v59, v60, v61
	global_store_dwordx2 v[68:69], v[58:59], off offset:32
	v_mul_f32_e32 v58, 0x3fb8aa3b, v222
	v_exp_f32_e32 v58, v58
	s_nop 0
	v_pk_mul_f32 v[48:49], v[58:59], v[48:49] op_sel_hi:[0,1]
	v_pk_mul_f32 v[46:47], v[58:59], v[46:47] op_sel_hi:[0,1]
	v_pk_mul_f32 v[52:53], v[58:59], v[52:53] op_sel_hi:[0,1]
	v_pk_mul_f32 v[50:51], v[58:59], v[50:51] op_sel_hi:[0,1]
	v_pk_mul_f32 v[56:57], v[58:59], v[56:57] op_sel_hi:[0,1]
	v_pk_mul_f32 v[54:55], v[58:59], v[54:55] op_sel_hi:[0,1]
	v_pk_mul_f32 v[44:45], v[58:59], v[44:45] op_sel_hi:[0,1]
	v_pk_mul_f32 v[42:43], v[58:59], v[42:43] op_sel_hi:[0,1]
	ds_read_b64_tr_b16 v[58:59], v213 offset:53248
	ds_read_b64_tr_b16 v[60:61], v213 offset:54336
	ds_read_b64_tr_b16 v[62:63], v70
	ds_read_b64_tr_b16 v[66:67], v70 offset:32
	ds_read_b64_tr_b16 v[64:65], v214
	ds_read_b64_tr_b16 v[68:69], v214 offset:32
	s_waitcnt lgkmcnt(1)
	v_mfma_f32_16x16x32_bf16 v[46:49], v[62:65], v[58:61], v[46:49]
	ds_read_b64_tr_b16 v[62:63], v70 offset:64
	ds_read_b64_tr_b16 v[64:65], v214 offset:64
	s_waitcnt lgkmcnt(0)
	v_mfma_f32_16x16x32_bf16 v[54:57], v[62:65], v[58:61], v[54:57]
	ds_read_b64_tr_b16 v[62:63], v70 offset:96
	ds_read_b64_tr_b16 v[64:65], v214 offset:96
	v_mfma_f32_16x16x32_bf16 v[50:53], v[66:69], v[58:61], v[50:53]
	s_waitcnt lgkmcnt(0)
	v_mfma_f32_16x16x32_bf16 v[42:45], v[62:65], v[58:61], v[42:45]
	ds_read_b64_tr_b16 v[58:59], v213 offset:61952
	ds_read_b64_tr_b16 v[60:61], v213 offset:63040
	ds_read_b64_tr_b16 v[62:63], v70 offset:4608
	ds_read_b64_tr_b16 v[64:65], v214 offset:4608
	s_waitcnt lgkmcnt(0)
	v_mfma_f32_16x16x32_bf16 v[46:49], v[62:65], v[58:61], v[46:49]
	ds_read_b64_tr_b16 v[62:63], v70 offset:4640
	ds_read_b64_tr_b16 v[64:65], v214 offset:4640
	s_waitcnt lgkmcnt(0)
	v_mfma_f32_16x16x32_bf16 v[50:53], v[62:65], v[58:61], v[50:53]
	ds_read_b64_tr_b16 v[62:63], v70 offset:4672
	ds_read_b64_tr_b16 v[64:65], v214 offset:4672
	s_waitcnt lgkmcnt(0)
	v_mfma_f32_16x16x32_bf16 v[54:57], v[62:65], v[58:61], v[54:57]
	ds_read_b64_tr_b16 v[62:63], v70 offset:4704
	ds_read_b64_tr_b16 v[64:65], v214 offset:4704
	s_waitcnt lgkmcnt(0)
	v_mfma_f32_16x16x32_bf16 v[42:45], v[62:65], v[58:61], v[42:45]
	ds_read_b64_tr_b16 v[58:59], v215 offset:53248
	ds_read_b64_tr_b16 v[60:61], v215 offset:54336
	ds_read_b64_tr_b16 v[62:63], v70 offset:9216
	ds_read_b64_tr_b16 v[64:65], v214 offset:9216
	s_waitcnt lgkmcnt(0)
	v_mfma_f32_16x16x32_bf16 v[46:49], v[62:65], v[58:61], v[46:49]
	ds_read_b64_tr_b16 v[62:63], v70 offset:9248
	ds_read_b64_tr_b16 v[64:65], v214 offset:9248
	s_waitcnt lgkmcnt(0)
	v_mfma_f32_16x16x32_bf16 v[50:53], v[62:65], v[58:61], v[50:53]
	ds_read_b64_tr_b16 v[62:63], v70 offset:9280
	ds_read_b64_tr_b16 v[64:65], v214 offset:9280
	s_waitcnt lgkmcnt(0)
	v_mfma_f32_16x16x32_bf16 v[54:57], v[62:65], v[58:61], v[54:57]
	ds_read_b64_tr_b16 v[62:63], v70 offset:9312
	ds_read_b64_tr_b16 v[64:65], v214 offset:9312
	s_waitcnt lgkmcnt(0)
	v_mfma_f32_16x16x32_bf16 v[42:45], v[62:65], v[58:61], v[42:45]
	ds_read_b64_tr_b16 v[58:59], v215 offset:61952
	ds_read_b64_tr_b16 v[60:61], v215 offset:63040
	ds_read_b64_tr_b16 v[62:63], v70 offset:13824
	ds_read_b64_tr_b16 v[64:65], v214 offset:13824
	s_waitcnt lgkmcnt(0)
	v_mfma_f32_16x16x32_bf16 v[46:49], v[62:65], v[58:61], v[46:49]
	ds_read_b64_tr_b16 v[62:63], v70 offset:13856
	ds_read_b64_tr_b16 v[64:65], v214 offset:13856
	s_waitcnt lgkmcnt(0)
	v_mfma_f32_16x16x32_bf16 v[50:53], v[62:65], v[58:61], v[50:53]
	ds_read_b64_tr_b16 v[62:63], v70 offset:13888
	ds_read_b64_tr_b16 v[64:65], v214 offset:13888
	s_waitcnt lgkmcnt(0)
	v_mfma_f32_16x16x32_bf16 v[54:57], v[62:65], v[58:61], v[54:57]
	ds_read_b64_tr_b16 v[62:63], v70 offset:13920
	ds_read_b64_tr_b16 v[64:65], v214 offset:13920
	s_waitcnt lgkmcnt(0)
	v_mfma_f32_16x16x32_bf16 v[42:45], v[62:65], v[58:61], v[42:45]
	s_cbranch_scc0 .LBB0_3639

; #define LAS __attribute__((address_space(3)))
; __global__ void __launch_bounds__(NWAVES * 64, 2) fwd(Args args_unused) {
;     extern __shared__ __attribute__((aligned(16))) unsigned char lds_raw[];
;     LAS unsigned char* const lds0 = (LAS unsigned char*)lds_raw;
;     volatile LAS unsigned* MISC = (volatile LAS unsigned*)(lds0 + MISC_OFF);
	.amdhsa_kernel _Z3fwd4Args
		.amdhsa_group_segment_fixed_size 0
		.amdhsa_private_segment_fixed_size 0
		.amdhsa_kernarg_size 616
		.amdhsa_user_sgpr_count 2
		.amdhsa_user_sgpr_dispatch_ptr 0
		.amdhsa_user_sgpr_queue_ptr 0
		.amdhsa_user_sgpr_kernarg_segment_ptr 1
		.amdhsa_user_sgpr_dispatch_id 0
		.amdhsa_user_sgpr_kernarg_preload_length 0
		.amdhsa_user_sgpr_kernarg_preload_offset 0
		.amdhsa_user_sgpr_private_segment_size 0
		.amdhsa_uses_dynamic_stack 0
		.amdhsa_enable_private_segment 0
		.amdhsa_system_sgpr_workgroup_id_x 1
		.amdhsa_system_sgpr_workgroup_id_y 0
		.amdhsa_system_sgpr_workgroup_id_z 0
		.amdhsa_system_sgpr_workgroup_info 0
		.amdhsa_system_vgpr_workitem_id 0
		.amdhsa_next_free_vgpr 256
		.amdhsa_next_free_sgpr 100
		.amdhsa_accum_offset 256
		.amdhsa_reserve_vcc 1
		.amdhsa_float_round_mode_32 0
		.amdhsa_float_round_mode_16_64 0
		.amdhsa_float_denorm_mode_32 3
		.amdhsa_float_denorm_mode_16_64 3
		.amdhsa_dx10_clamp 1
		.amdhsa_ieee_mode 1
		.amdhsa_fp16_overflow 0
		.amdhsa_tg_split 0
		.amdhsa_exception_fp_ieee_invalid_op 0
		.amdhsa_exception_fp_denorm_src 0
		.amdhsa_exception_fp_ieee_div_zero 0
		.amdhsa_exception_fp_ieee_overflow 0
		.amdhsa_exception_fp_ieee_underflow 0
		.amdhsa_exception_fp_ieee_inexact 0
		.amdhsa_exception_int_div_zero 0
	.end_amdhsa_kernel

; #define LAS __attribute__((address_space(3)))
; __global__ void __launch_bounds__(NWAVES * 64, 2) fwd(Args args_unused) {
;     extern __shared__ __attribute__((aligned(16))) unsigned char lds_raw[];
;     LAS unsigned char* const lds0 = (LAS unsigned char*)lds_raw;
;     volatile LAS unsigned* MISC = (volatile LAS unsigned*)(lds0 + MISC_OFF);
amdhsa.kernels:
  - .agpr_count:     0
    .args:
      - .offset:         0
        .size:           360
        .value_kind:     by_value
      - .offset:         360
        .size:           4
        .value_kind:     hidden_block_count_x
      - .offset:         364
        .size:           4
        .value_kind:     hidden_block_count_y
      - .offset:         368
        .size:           4
        .value_kind:     hidden_block_count_z
      - .offset:         372
        .size:           2
        .value_kind:     hidden_group_size_x
      - .offset:         374
        .size:           2
        .value_kind:     hidden_group_size_y
      - .offset:         376
        .size:           2
        .value_kind:     hidden_group_size_z
      - .offset:         378
        .size:           2
        .value_kind:     hidden_remainder_x
      - .offset:         380
        .size:           2
        .value_kind:     hidden_remainder_y
      - .offset:         382
        .size:           2
        .value_kind:     hidden_remainder_z
      - .offset:         400
        .size:           8
        .value_kind:     hidden_global_offset_x
      - .offset:         408
        .size:           8
        .value_kind:     hidden_global_offset_y
      - .offset:         416
        .size:           8
        .value_kind:     hidden_global_offset_z
      - .offset:         424
        .size:           2
        .value_kind:     hidden_grid_dims
      - .offset:         480
        .size:           4
        .value_kind:     hidden_dynamic_lds_size
    .group_segment_fixed_size: 0
    .kernarg_segment_align: 8
    .kernarg_segment_size: 616
    .language:       OpenCL C
    .language_version:
      - 2
      - 0
    .max_flat_workgroup_size: 512
    .name:           _Z3fwd4Args
    .private_segment_fixed_size: 0
    .sgpr_count:     104
    .sgpr_spill_count: 104
    .symbol:         _Z3fwd4Args.kd
    .uniform_work_group_size: 1
    .uses_dynamic_stack: false
    .vgpr_count:     256
    .vgpr_spill_count: 0
    .wavefront_size: 64
